# attention (P3) output stores widened from 8 x 8-byte to 4 x 16-byte per lane via v_permlane32_swap (halves the partial-line write requests), counted vmcnt waits re-derived
# speedup vs baseline: 1.0151x; 1.0151x over previous
.LBB0_727:
	s_or_b64 exec, exec, s[6:7]
	s_waitcnt vmcnt(7)
	v_mov_b64_e32 v[76:77], v[128:129]
	s_waitcnt vmcnt(6)
	v_mov_b64_e32 v[80:81], v[124:125]
	s_waitcnt vmcnt(5)
	v_mov_b64_e32 v[84:85], v[120:121]
	s_waitcnt vmcnt(4)
	v_mov_b64_e32 v[88:89], v[116:117]
	s_andn2_b64 vcc, exec, s[4:5]
	v_mov_b64_e32 v[78:79], v[130:131]
	v_mov_b64_e32 v[82:83], v[126:127]
	v_mov_b64_e32 v[86:87], v[122:123]
	v_mov_b64_e32 v[90:91], v[118:119]
	s_mov_b32 s51, s89
	s_cbranch_vccz .LBB0_878

.LBB0_875:
	v_mov_b32_e32 v153, v34
	v_mov_b32_e32 v194, v35
	ds_read_b128 v[32:35], v152
	ds_read_b128 v[140:143], v152 offset:32
	ds_read_b128 v[136:139], v152 offset:64
	ds_read_b128 v[132:135], v152 offset:96
	s_waitcnt lgkmcnt(3)
	v_mfma_f32_32x32x16_bf16 v[32:47], v[32:35], v[76:79], 0
	v_add_u32_e32 v195, 27, v192
	v_add_u32_e32 v196, v146, v151
	v_add_u32_e32 v197, 25, v192
	v_add_u32_e32 v198, 24, v192
	v_cmp_lt_u32_e32 vcc, s76, v196
	v_cmp_gt_u32_e64 s[36:37], s68, v195
	v_add_u32_e32 v199, 19, v192
	s_waitcnt lgkmcnt(2)
	v_mfma_f32_32x32x16_bf16 v[32:47], v[140:143], v[80:83], v[32:47]
	v_add_u32_e32 v200, 18, v192
	v_cmp_gt_u32_e64 s[6:7], s68, v197
	v_cmp_gt_u32_e64 s[8:9], s68, v198
	v_add_u32_e32 v201, 17, v192
	v_add_u32_e32 v202, 16, v192
	v_cmp_gt_u32_e64 s[10:11], s68, v199
	v_cmp_gt_u32_e64 s[12:13], s68, v200
	s_waitcnt lgkmcnt(1)
	v_mfma_f32_32x32x16_bf16 v[32:47], v[136:139], v[84:87], v[32:47]
	v_add_u32_e32 v203, 11, v192
	v_add_u32_e32 v204, 10, v192
	v_cmp_gt_u32_e64 s[14:15], s68, v201
	v_cmp_gt_u32_e64 s[16:17], s68, v202
	v_add_u32_e32 v205, 9, v192
	v_add_u32_e32 v206, 8, v192
	v_cmp_gt_u32_e64 s[18:19], s68, v203
	s_waitcnt lgkmcnt(0)
	v_mfma_f32_32x32x16_bf16 v[32:47], v[132:135], v[88:91], v[32:47]
	v_cmp_gt_u32_e64 s[20:21], s68, v204
	v_add_u32_e32 v207, 3, v192
	v_add_u32_e32 v208, 2, v192
	v_cmp_gt_u32_e64 s[22:23], s68, v205
	v_cmp_gt_u32_e64 s[24:25], s68, v206
	v_add_u32_e32 v209, 1, v192
	v_cmp_gt_u32_e64 s[26:27], s68, v207
	s_nop 4
	v_cndmask_b32_e64 v32, v190, v32, s[36:37]
	v_cndmask_b32_e32 v33, v190, v33, vcc
	v_cndmask_b32_e64 v132, v190, v34, s[6:7]
	v_cndmask_b32_e64 v35, v190, v35, s[8:9]
	v_max3_f32 v34, v32, s69, v33
	v_cndmask_b32_e64 v36, v190, v36, s[10:11]
	v_cndmask_b32_e64 v37, v190, v37, s[12:13]
	v_max3_f32 v34, v34, v132, v35
	v_cndmask_b32_e64 v38, v190, v38, s[14:15]
	v_cndmask_b32_e64 v39, v190, v39, s[16:17]
	v_max3_f32 v34, v34, v36, v37
	v_cndmask_b32_e64 v40, v190, v40, s[18:19]
	v_cndmask_b32_e64 v41, v190, v41, s[20:21]
	v_max3_f32 v34, v34, v38, v39
	v_cmp_gt_u32_e64 s[28:29], s68, v208
	v_cndmask_b32_e64 v42, v190, v42, s[22:23]
	v_cndmask_b32_e64 v43, v190, v43, s[24:25]
	v_max3_f32 v34, v34, v40, v41
	v_cmp_gt_u32_e64 s[30:31], s68, v209
	v_cmp_gt_u32_e64 s[34:35], s68, v192
	v_cndmask_b32_e64 v44, v190, v44, s[26:27]
	v_cndmask_b32_e64 v45, v190, v45, s[28:29]
	v_max3_f32 v34, v34, v42, v43
	v_cndmask_b32_e64 v46, v190, v46, s[30:31]
	v_cndmask_b32_e64 v47, v190, v47, s[34:35]
	v_max3_f32 v34, v34, v44, v45
	v_max3_f32 v34, v34, v46, v47
	ds_bpermute_b32 v133, v73, v34
	v_add_u32_e32 v210, v146, v193
	v_add_u32_e32 v211, 8, v210
	v_add_u32_e32 v212, 16, v210
	v_add_u32_e32 v213, 24, v210
	s_waitcnt lgkmcnt(0)
	v_max3_f32 v34, v153, v34, v133
	v_sub_f32_e32 v32, v32, v34
	v_sub_f32_e32 v133, v153, v34
	v_sub_f32_e32 v33, v33, v34
	v_mul_f32_e32 v32, 0x3fb8aa3b, v32
	v_sub_f32_e32 v132, v132, v34
	v_mul_f32_e32 v133, 0x3fb8aa3b, v133
	v_mul_f32_e32 v33, 0x3fb8aa3b, v33
	v_exp_f32_e32 v134, v32
	v_sub_f32_e32 v35, v35, v34
	v_mul_f32_e32 v132, 0x3fb8aa3b, v132
	v_exp_f32_e32 v33, v33
	v_exp_f32_e32 v32, v133
	v_sub_f32_e32 v36, v36, v34
	v_mul_f32_e32 v35, 0x3fb8aa3b, v35
	v_exp_f32_e32 v153, v132
	v_sub_f32_e32 v37, v37, v34
	v_mul_f32_e32 v36, 0x3fb8aa3b, v36
	v_exp_f32_e32 v35, v35
	v_xor_b32_e32 v214, v210, v172
	v_xor_b32_e32 v141, v211, v172
	v_xor_b32_e32 v142, v212, v172
	v_xor_b32_e32 v143, v213, v172
	v_sub_f32_e32 v38, v38, v34
	v_sub_f32_e32 v39, v39, v34
	v_sub_f32_e32 v40, v40, v34
	v_sub_f32_e32 v41, v41, v34
	v_sub_f32_e32 v42, v42, v34
	v_sub_f32_e32 v43, v43, v34
	v_sub_f32_e32 v44, v44, v34
	v_sub_f32_e32 v45, v45, v34
	v_sub_f32_e32 v46, v46, v34
	v_sub_f32_e32 v47, v47, v34
	v_mul_f32_e32 v37, 0x3fb8aa3b, v37
	v_exp_f32_e32 v195, v36
	v_add_f32_e32 v207, 0, v134
	v_xor_b32_e32 v210, v210, v174
	v_lshl_add_u32 v140, v214, 1, v171
	v_xor_b32_e32 v211, v211, v174
	v_xor_b32_e32 v136, v213, v174
	v_lshl_add_u32 v137, v141, 1, v171
	v_lshl_add_u32 v138, v142, 1, v171
	v_lshl_add_u32 v139, v143, 1, v171
	v_mul_f32_e32 v38, 0x3fb8aa3b, v38
	v_mul_f32_e32 v39, 0x3fb8aa3b, v39
	v_mul_f32_e32 v40, 0x3fb8aa3b, v40
	v_mul_f32_e32 v41, 0x3fb8aa3b, v41
	v_mul_f32_e32 v42, 0x3fb8aa3b, v42
	v_mul_f32_e32 v43, 0x3fb8aa3b, v43
	v_mul_f32_e32 v44, 0x3fb8aa3b, v44
	v_mul_f32_e32 v45, 0x3fb8aa3b, v45
	v_mul_f32_e32 v46, 0x3fb8aa3b, v46
	v_mul_f32_e32 v47, 0x3fb8aa3b, v47
	v_exp_f32_e32 v196, v37
	v_pk_mul_f32 v[16:17], v[16:17], v[32:33] op_sel_hi:[1,0]
	v_pk_mul_f32 v[0:1], v[0:1], v[32:33] op_sel_hi:[1,0]
	v_pk_mul_f32 v[18:19], v[18:19], v[32:33] op_sel_hi:[1,0]
	v_pk_mul_f32 v[2:3], v[2:3], v[32:33] op_sel_hi:[1,0]
	v_pk_mul_f32 v[20:21], v[20:21], v[32:33] op_sel_hi:[1,0]
	v_pk_mul_f32 v[4:5], v[4:5], v[32:33] op_sel_hi:[1,0]
	v_pk_mul_f32 v[22:23], v[22:23], v[32:33] op_sel_hi:[1,0]
	v_pk_mul_f32 v[6:7], v[6:7], v[32:33] op_sel_hi:[1,0]
	v_cvt_pk_bf16_f32 v36, v134, v33
	v_pk_mul_f32 v[24:25], v[24:25], v[32:33] op_sel_hi:[1,0]
	v_pk_mul_f32 v[26:27], v[26:27], v[32:33] op_sel_hi:[1,0]
	v_pk_mul_f32 v[28:29], v[28:29], v[32:33] op_sel_hi:[1,0]
	v_pk_mul_f32 v[30:31], v[30:31], v[32:33] op_sel_hi:[1,0]
	v_pk_mul_f32 v[8:9], v[8:9], v[32:33] op_sel_hi:[1,0]
	v_pk_mul_f32 v[10:11], v[10:11], v[32:33] op_sel_hi:[1,0]
	v_pk_mul_f32 v[12:13], v[12:13], v[32:33] op_sel_hi:[1,0]
	v_pk_mul_f32 v[14:15], v[14:15], v[32:33] op_sel_hi:[1,0]
	v_add_f32_e32 v33, v33, v207
	v_lshl_add_u32 v210, v210, 1, v173
	v_lshl_add_u32 v141, v211, 1, v173
	v_lshl_add_u32 v143, v136, 1, v173
	v_exp_f32_e32 v197, v38
	v_exp_f32_e32 v198, v39
	v_exp_f32_e32 v199, v40
	v_exp_f32_e32 v200, v41
	v_exp_f32_e32 v201, v42
	v_exp_f32_e32 v202, v43
	v_exp_f32_e32 v203, v44
	v_exp_f32_e32 v204, v45
	v_exp_f32_e32 v205, v46
	v_exp_f32_e32 v206, v47
	v_cvt_pk_bf16_f32 v37, v153, v35
	v_cvt_pk_bf16_f32 v38, v195, v196
	v_cvt_pk_bf16_f32 v39, v197, v198
	v_cvt_pk_bf16_f32 v40, v199, v200
	v_cvt_pk_bf16_f32 v41, v201, v202
	v_cvt_pk_bf16_f32 v42, v203, v204
	v_cvt_pk_bf16_f32 v43, v205, v206
	ds_read_b64 v[44:45], v140 offset:55296
	ds_read_b64 v[46:47], v137 offset:55296
	ds_read_b64 v[132:133], v138 offset:55296
	ds_read_b64 v[134:135], v139 offset:55296
	ds_read_b64 v[136:137], v210 offset:55296
	ds_read_b64 v[138:139], v141 offset:55296
	v_add_f32_e32 v33, v153, v33
	v_add_f32_e32 v33, v35, v33
	v_add_f32_e32 v33, v195, v33
	v_add_f32_e32 v33, v196, v33
	v_add_f32_e32 v33, v197, v33
	s_waitcnt lgkmcnt(4)
	v_mfma_f32_32x32x16_bf16 v[16:31], v[44:47], v[36:39], v[16:31]
	v_add_f32_e32 v33, v198, v33
	v_xor_b32_e32 v212, v212, v174
	v_add_f32_e32 v33, v199, v33
	v_lshl_add_u32 v142, v212, 1, v173
	v_add_f32_e32 v33, v200, v33
	ds_read_b64 v[44:45], v142 offset:55296
	ds_read_b64 v[46:47], v143 offset:55296
	v_add_f32_e32 v33, v201, v33
	s_waitcnt lgkmcnt(2)
	v_mfma_f32_32x32x16_bf16 v[0:15], v[136:139], v[36:39], v[0:15]
	v_add_f32_e32 v33, v202, v33
	v_add_f32_e32 v33, v203, v33
	v_add_f32_e32 v33, v204, v33
	v_add_f32_e32 v33, v205, v33
	v_add_f32_e32 v33, v206, v33
	ds_bpermute_b32 v35, v73, v33
	v_add_u32_e32 v75, 1, v75
	v_mfma_f32_32x32x16_bf16 v[16:31], v[132:135], v[40:43], v[16:31]
	v_cmp_lt_i32_e32 vcc, 3, v75
	v_add_u32_e32 v151, 32, v151
	s_waitcnt lgkmcnt(0)
	v_add_f32_e32 v35, v33, v35
	v_add_u32_e32 v193, 32, v193
	v_add_u32_e32 v152, 0x1200, v152
	s_or_b64 s[52:53], vcc, s[52:53]
	v_subrev_u32_e32 v192, 32, v192
	v_mfma_f32_32x32x16_bf16 v[0:15], v[44:47], v[40:43], v[0:15]
	v_fmac_f32_e32 v35, v194, v32
	s_andn2_b64 exec, exec, s[52:53]
	s_cbranch_execnz .LBB0_875
	s_or_b64 exec, exec, s[52:53]
	v_div_scale_f32 v32, s[6:7], v35, v35, 1.0
	v_rcp_f32_e32 v33, v32
	s_lshl_b32 s8, s51, 4
	s_and_b32 s9, s8, 0x1800
	s_bfe_u32 s8, s51, 0x40003
	v_fma_f32 v36, -v32, v33, 1.0
	v_fmac_f32_e32 v33, v36, v33
	v_div_scale_f32 v36, vcc, 1.0, v35, 1.0
	v_mul_f32_e32 v37, v36, v33
	v_fma_f32 v38, -v32, v37, v36
	v_fmac_f32_e32 v37, v38, v33
	s_ashr_i32 s51, s50, 31
	v_fma_f32 v32, -v32, v37, v36
	s_lshl_b64 s[6:7], s[50:51], 13
	v_mov_b32_e32 v75, v72
	v_div_fmas_f32 v32, v32, v33, v37
	s_or_b32 s6, s6, s9
	v_div_fixup_f32 v40, v32, v35, 1.0
	v_lshl_add_u64 v[32:33], s[6:7], 0, v[74:75]
	v_lshlrev_b64 v[36:37], 11, v[32:33]
	v_lshl_add_u64 v[36:37], s[42:43], 0, v[36:37]
	s_lshl_b32 s46, s8, 7
	v_lshl_add_u64 v[36:37], v[36:37], 0, s[46:47]
	v_lshlrev_b32_e32 v38, 2, v146
	v_mov_b32_e32 v39, v72
	v_lshl_add_u64 v[36:37], v[36:37], 0, v[38:39]
	v_mul_f32_e32 v16, v16, v40
	v_mul_f32_e32 v17, v17, v40
	v_mul_f32_e32 v18, v18, v40
	v_mul_f32_e32 v19, v19, v40
	v_mul_f32_e32 v20, v20, v40
	v_mul_f32_e32 v21, v21, v40
	v_mul_f32_e32 v22, v22, v40
	v_mul_f32_e32 v23, v23, v40
	v_mul_f32_e32 v24, v24, v40
	v_mul_f32_e32 v25, v25, v40
	v_mul_f32_e32 v26, v26, v40
	v_mul_f32_e32 v27, v27, v40
	v_mul_f32_e32 v28, v28, v40
	v_mul_f32_e32 v29, v29, v40
	v_mul_f32_e32 v30, v30, v40
	v_mul_f32_e32 v31, v31, v40
	v_mul_f32_e32 v0, v0, v40
	v_mul_f32_e32 v1, v1, v40
	v_mul_f32_e32 v2, v2, v40
	v_mul_f32_e32 v3, v3, v40
	v_mul_f32_e32 v4, v4, v40
	v_mul_f32_e32 v5, v5, v40
	v_mul_f32_e32 v6, v6, v40
	v_mul_f32_e32 v7, v7, v40
	v_mul_f32_e32 v8, v8, v40
	v_mul_f32_e32 v9, v9, v40
	v_mul_f32_e32 v10, v10, v40
	v_mul_f32_e32 v11, v11, v40
	v_mul_f32_e32 v12, v12, v40
	v_mul_f32_e32 v13, v13, v40
	v_mul_f32_e32 v14, v14, v40
	v_mul_f32_e32 v15, v15, v40
	v_cvt_pk_bf16_f32 v16, v16, v17
	v_cvt_pk_bf16_f32 v17, v18, v19
	v_cvt_pk_bf16_f32 v18, v20, v21
	v_cvt_pk_bf16_f32 v19, v22, v23
	v_cvt_pk_bf16_f32 v20, v24, v25
	v_cvt_pk_bf16_f32 v21, v26, v27
	v_cvt_pk_bf16_f32 v22, v28, v29
	v_cvt_pk_bf16_f32 v23, v30, v31
	v_cvt_pk_bf16_f32 v24, v0, v1
	v_cvt_pk_bf16_f32 v25, v2, v3
	v_cvt_pk_bf16_f32 v26, v4, v5
	v_cvt_pk_bf16_f32 v27, v6, v7
	v_cvt_pk_bf16_f32 v28, v8, v9
	v_cvt_pk_bf16_f32 v29, v10, v11
	v_cvt_pk_bf16_f32 v30, v12, v13
	v_cvt_pk_bf16_f32 v31, v14, v15
	s_nop 1
	v_permlane32_swap_b32_e32 v16, v18
	v_permlane32_swap_b32_e32 v17, v19
	v_permlane32_swap_b32_e32 v20, v22
	v_permlane32_swap_b32_e32 v21, v23
	v_permlane32_swap_b32_e32 v24, v26
	v_permlane32_swap_b32_e32 v25, v27
	v_permlane32_swap_b32_e32 v28, v30
	v_permlane32_swap_b32_e32 v29, v31
	global_store_dwordx4 v[36:37], v[16:19], off
	global_store_dwordx4 v[36:37], v[20:23], off offset:32
	global_store_dwordx4 v[36:37], v[24:27], off offset:64
	global_store_dwordx4 v[36:37], v[28:31], off offset:96
	s_and_saveexec_b64 s[6:7], s[2:3]
	s_cbranch_execz .LBB0_727
	v_cmp_gt_f32_e32 vcc, s77, v35
	s_lshl_b32 s46, s8, 2
	s_nop 0
	v_cndmask_b32_e64 v0, 0, 32, vcc
	v_ldexp_f32 v0, v35, v0
	v_log_f32_e32 v0, v0
	v_cndmask_b32_e32 v1, 0, v191, vcc
	v_mul_f32_e32 v2, 0x3f317217, v0
	v_fma_f32 v2, v0, s78, -v2
	v_fmac_f32_e32 v2, 0x3377d1cf, v0
	v_fmac_f32_e32 v2, 0x3f317217, v0
	v_cmp_lt_f32_e64 vcc, |v0|, s79
	s_nop 1
	v_cndmask_b32_e32 v0, v0, v2, vcc
	v_sub_f32_e32 v0, v0, v1
	v_add_f32_e32 v2, v34, v0
	v_lshlrev_b64 v[0:1], 6, v[32:33]
	v_lshl_add_u64 v[0:1], s[44:45], 0, v[0:1]
	v_lshl_add_u64 v[0:1], v[0:1], 0, s[46:47]
	global_store_dword v[0:1], v2, off
	s_branch .LBB0_727
